# attention step re-laid so the common path falls through (rare blocks out of line): ~6 taken branches per step removed; on top of conflict-free LDS layouts
# baseline (speedup 1.0000x reference)
.LBB0_121:
	s_lshl_b32 s0, s14, 11
	s_waitcnt vmcnt(0)
	v_add_u32_e32 v0, s0, v79
	v_ashrrev_i32_e32 v1, 31, v0
	v_readlane_b32 s4, v251, 6
	v_lshlrev_b64 v[0:1], 12, v[0:1]
	v_readlane_b32 s5, v251, 7
	s_lshl_b32 s26, s13, 1
	v_readlane_b32 s2, v251, 8
	v_lshl_add_u64 v[0:1], s[4:5], 0, v[0:1]
	v_lshl_add_u64 v[0:1], v[0:1], 0, s[26:27]
	v_readlane_b32 s3, v251, 9
	v_lshl_add_u64 v[70:71], v[0:1], 0, v[152:153]
	v_add_u32_e32 v2, s13, v79
	v_mov_b64_e32 v[0:1], s[2:3]
	v_mad_i64_i32 v[0:1], s[2:3], v2, s23, v[0:1]
	s_ashr_i32 s1, s0, 31
	v_lshl_add_u64 v[0:1], s[0:1], 1, v[0:1]
	v_lshl_add_u64 v[72:73], v[0:1], 0, v[152:153]
	global_load_dwordx4 v[0:3], v[70:71], off offset:2048
	global_load_dwordx4 v[4:7], v[72:73], off
	global_load_dwordx4 v[8:11], v[72:73], off offset:128
	s_mov_b32 s1, 0x40000
	v_add_co_u32_e32 v12, vcc, s1, v70
	s_add_i32 s2, s10, s0
	s_nop 0
	v_addc_co_u32_e32 v13, vcc, 0, v71, vcc
	global_load_dwordx4 v[12:15], v[12:13], off offset:2048
	v_or_b32_e32 v20, s2, v63
	v_ashrrev_i32_e32 v21, 31, v20
	v_add_co_u32_e32 v24, vcc, s25, v70
	v_lshlrev_b64 v[20:21], 12, v[20:21]
	s_nop 0
	v_addc_co_u32_e32 v25, vcc, 0, v71, vcc
	v_lshl_add_u64 v[20:21], s[4:5], 0, v[20:21]
	v_add_co_u32_e32 v26, vcc, s31, v70
	v_add_u32_e32 v96, 0x18800, v235
	v_lshl_add_u64 v[20:21], v[20:21], 0, s[26:27]
	v_addc_co_u32_e32 v27, vcc, 0, v71, vcc
	v_add_u32_e32 v93, 0x12000, v92
	v_add_u32_e32 v94, 0x14000, v235
	v_add_u32_e32 v95, 0x16800, v92
	global_load_dwordx4 v[16:19], v[72:73], off offset:256
	v_lshl_add_u64 v[32:33], v[56:57], 1, v[20:21]
	global_load_dwordx4 v[20:23], v[72:73], off offset:384
	global_load_dwordx4 v[28:31], v[24:25], off offset:2048
	s_nop 0
	global_load_dwordx4 v[24:27], v[26:27], off offset:2048
	v_mov_b32_e32 v100, 0
	s_mov_b32 s1, 0
	s_or_b32 s0, s0, s8
	v_lshl_add_u64 v[74:75], v[58:59], 0, s[26:27]
	v_lshl_add_u64 v[76:77], v[60:61], 0, s[26:27]
	v_mov_b32_e32 v101, 0xf149f2ca
	s_mov_b32 s15, 4
	s_mov_b32 s5, 8
	s_mov_b32 s3, -3
	v_mov_b32_e32 v97, 0
	v_mov_b32_e32 v98, 8
	v_mov_b32_e32 v99, 0
	s_mov_b32 s14, 0
	s_mov_b32 s13, s9
	s_mov_b32 s4, 0
	s_mov_b32 s16, 4
	v_mov_b32_e32 v34, v100
	v_mov_b32_e32 v35, v100
	v_mov_b32_e32 v36, v100
	v_mov_b32_e32 v37, v100
	v_mov_b32_e32 v38, v100
	v_mov_b32_e32 v39, v100
	v_mov_b32_e32 v40, v100
	v_mov_b32_e32 v41, v100
	v_mov_b32_e32 v42, v100
	v_mov_b32_e32 v43, v100
	v_mov_b32_e32 v44, v100
	v_mov_b32_e32 v45, v100
	v_mov_b32_e32 v46, v100
	v_mov_b32_e32 v47, v100
	s_waitcnt vmcnt(0)
	ds_write_b128 v96, v[8:11]
	ds_write_b128 v94, v[4:7]
	ds_write_b128 v93, v[0:3]
	s_waitcnt vmcnt(4)
	ds_write_b128 v95, v[12:15]
	s_waitcnt lgkmcnt(0)
	s_barrier
	global_load_dwordx4 v[0:3], v[32:33], off
	global_load_dwordx4 v[4:7], v[32:33], off offset:64
	v_mov_b32_e32 v8, v153
	v_mov_b32_e32 v9, v153
	v_mov_b32_e32 v10, v153
	v_mov_b32_e32 v11, v153
	v_mov_b32_e32 v12, v153
	v_mov_b32_e32 v13, v153
	v_mov_b32_e32 v14, v153
	v_mov_b32_e32 v15, v153
	v_mov_b32_e32 v32, 0
	v_mov_b32_e32 v33, v100
	v_add_u32_e32 v226, 0x1b000, v92
	v_add_u32_e32 v227, 0x1d000, v235
	v_mov_b32_e32 v144, 0x3f803f80
	v_mov_b32_e32 v145, v144
	v_mov_b32_e32 v146, v144
	v_mov_b32_e32 v147, v144
	v_sub_u32_e32 v102, v97, v99
	v_add_u32_e32 v102, s14, v102
	v_cmp_gt_u32_e32 vcc, 8, v102
	s_cbranch_vccz .Lpf_skip_init
	v_mad_u32_u24 v103, v102, s34, v67
	v_subrev_u32_e32 v120, s13, v99
	ds_read_b128 v[166:169], v103 offset:3072
	ds_read_b128 v[174:177], v103 offset:5120
	ds_read_b128 v[170:173], v103 offset:4096
	ds_read_b128 v[178:181], v103 offset:6144
	v_add3_u32 v120, v120, v102, 7
	ds_read_b128 v[182:185], v81 offset:0
	ds_read_b128 v[190:193], v81 offset:256
	ds_read_b128 v[186:189], v82 offset:0
	ds_read_b128 v[194:197], v82 offset:256
	v_lshl_add_u32 v120, v120, 8, v162
	ds_read_b128 v[112:115], v120
	ds_read_b128 v[116:119], v120 offset:16
	s_waitcnt lgkmcnt(10)
.Lpf_done_init:
	s_branch .LBB0_123
.LBB0_122:
	s_waitcnt vmcnt(4)
	ds_write_b128 v95, v[48:51]
	ds_write_b128 v96, v[52:55]
	v_sub_u32_e32 v102, v97, v99
	v_add_u32_e32 v102, s14, v102
	v_cmp_gt_u32_e32 vcc, 8, v102
	s_cbranch_vccz .Lpf_skip_a
	v_mad_u32_u24 v103, v102, s34, v67
	v_subrev_u32_e32 v120, s13, v99
	ds_read_b128 v[166:169], v103 offset:3072
	ds_read_b128 v[174:177], v103 offset:5120
	ds_read_b128 v[170:173], v103 offset:4096
	ds_read_b128 v[178:181], v103 offset:6144
	v_add3_u32 v120, v120, v102, 7
	ds_read_b128 v[182:185], v81 offset:0
	ds_read_b128 v[190:193], v81 offset:256
	ds_read_b128 v[186:189], v82 offset:0
	ds_read_b128 v[194:197], v82 offset:256
	v_lshl_add_u32 v120, v120, 8, v162
	ds_read_b128 v[112:115], v120
	ds_read_b128 v[116:119], v120 offset:16
	s_waitcnt lgkmcnt(10)
.Lpf_done_a:
	s_barrier
	s_add_i32 s3, s3, 3
	s_cmpk_gt_u32 s3, 0x89
	s_cbranch_scc1 .LBB0_110
.LBB0_123:
	s_cmp_lt_i32 s4, 16
	s_cselect_b32 s18, s16, 0
	s_ashr_i32 s19, s18, 31
	s_lshl_b64 s[20:21], s[18:19], 18
	s_lshl_b32 s18, s18, 6
	s_ashr_i32 s19, s18, 31
	v_lshl_add_u64 v[48:49], v[70:71], 0, s[20:21]
	v_lshl_add_u64 v[52:53], s[18:19], 1, v[72:73]
	global_load_dwordx4 v[48:51], v[48:49], off offset:2048
	s_nop 0
	global_load_dwordx4 v[52:55], v[52:53], off
	s_add_i32 s17, s15, 1
	v_cmp_lt_i32_e32 vcc, s17, v98
	s_cbranch_vccz .Lwrap_a

.LBB0_126:
	s_cmp_lg_u32 s14, 0
	s_cbranch_scc0 .LBB0_159
	s_add_i32 s16, s5, -2
	s_cmp_lg_u32 s14, s16
	s_cbranch_scc0 .LBB0_128
.LBB0_129:
	v_sub_u32_e32 v102, v97, v99
	v_add_u32_e32 v102, s14, v102
	v_cmp_lt_u32_e32 vcc, 7, v102
	s_cbranch_vccnz .Linact_a
	v_lshl_add_u32 v137, v102, 12, v78
	ds_read_b128 v[198:201], v137 offset:39936
	ds_read_b128 v[202:205], v137 offset:40960
	ds_read_b128 v[206:209], v137 offset:41984
	ds_read_b128 v[232:235], v137 offset:43008
	s_waitcnt lgkmcnt(4)
	v_mfma_f32_16x16x32_bf16 v[104:107], v[166:169], v[8:11], v[140:143]
	v_add_f32_e32 v112, v112, v148
	v_add_f32_e32 v113, v113, v149
	v_mfma_f32_16x16x32_bf16 v[108:111], v[174:177], v[8:11], v[140:143]
	v_add_f32_e32 v114, v114, v150
	v_add_f32_e32 v115, v115, v151
	v_mfma_f32_16x16x32_bf16 v[104:107], v[170:173], v[12:15], v[104:107]
	v_add_f32_e32 v116, v116, v158
	v_add_f32_e32 v117, v117, v159
	v_mfma_f32_16x16x32_bf16 v[108:111], v[178:181], v[12:15], v[108:111]
	v_add_f32_e32 v118, v118, v160
	v_add_f32_e32 v119, v119, v161
	ds_read_b128 v[236:239], v83 offset:0
	ds_read_b128 v[240:243], v83 offset:256
	ds_read_b128 v[244:247], v83 offset:512
	ds_read_b128 v[228:231], v83 offset:768
	v_mfma_f32_16x16x32_bf16 v[112:115], v[182:185], v[8:11], v[112:115]
	v_mfma_f32_16x16x32_bf16 v[116:119], v[190:193], v[8:11], v[116:119]
	v_mfma_f32_16x16x32_bf16 v[112:115], v[186:189], v[12:15], v[112:115]
	v_mfma_f32_16x16x32_bf16 v[116:119], v[194:197], v[12:15], v[116:119]
	v_max3_f32 v121, v104, v105, v106
	v_max3_f32 v122, v108, v109, v110
	v_max3_f32 v121, v121, v107, v111
	s_nop 3
	v_max3_f32 v123, v112, v113, v114
	v_max3_f32 v122, v122, v116, v117
	v_max3_f32 v121, v121, v115, v118
	v_max3_f32 v121, v121, v122, v123
	v_max_f32_e32 v121, v121, v119
	v_cmp_lt_f32_e32 vcc, 0x41000000, v121
	s_cbranch_vccnz .Lrare_a
.Lback_a:
	v_exp_f32_e32 v104, v104
	v_exp_f32_e32 v105, v105
	v_exp_f32_e32 v106, v106
	v_exp_f32_e32 v107, v107
	v_exp_f32_e32 v108, v108
	v_exp_f32_e32 v109, v109
	v_exp_f32_e32 v110, v110
	v_exp_f32_e32 v111, v111
	v_exp_f32_e32 v112, v112
	v_exp_f32_e32 v113, v113
	v_exp_f32_e32 v114, v114
	v_exp_f32_e32 v115, v115
	v_exp_f32_e32 v116, v116
	v_exp_f32_e32 v117, v117
	v_exp_f32_e32 v118, v118
	v_exp_f32_e32 v119, v119
	v_cvt_pk_bf16_f32 v124, v104, v105
	v_cvt_pk_bf16_f32 v125, v106, v107
	v_cvt_pk_bf16_f32 v126, v108, v109
	v_cvt_pk_bf16_f32 v127, v110, v111
	v_cvt_pk_bf16_f32 v128, v112, v113
	v_cvt_pk_bf16_f32 v129, v114, v115
	v_cvt_pk_bf16_f32 v130, v116, v117
	v_cvt_pk_bf16_f32 v131, v118, v119
	s_waitcnt lgkmcnt(4)
	v_mfma_f32_16x16x32_bf16 v[32:35], v[198:201], v[124:127], v[32:35]
	v_mfma_f32_16x16x32_bf16 v[36:39], v[202:205], v[124:127], v[36:39]
	v_mfma_f32_16x16x32_bf16 v[40:43], v[206:209], v[124:127], v[40:43]
	v_mfma_f32_16x16x32_bf16 v[44:47], v[232:235], v[124:127], v[44:47]
	v_mfma_f32_16x16x32_bf16 v[132:135], v[144:147], v[124:127], v[132:135]
	s_waitcnt lgkmcnt(0)
	v_mfma_f32_16x16x32_bf16 v[32:35], v[236:239], v[128:131], v[32:35]
	v_mfma_f32_16x16x32_bf16 v[36:39], v[240:243], v[128:131], v[36:39]
	v_mfma_f32_16x16x32_bf16 v[132:135], v[144:147], v[128:131], v[132:135]
	v_mfma_f32_16x16x32_bf16 v[40:43], v[244:247], v[128:131], v[40:43]
	v_mfma_f32_16x16x32_bf16 v[44:47], v[228:231], v[128:131], v[44:47]
	s_add_i32 s16, s5, -1
	s_cmp_lg_u32 s14, s16
	s_cbranch_scc0 .LBB0_153
.LBB0_131:
	s_add_i32 s14, s14, 1
	s_cmp_lt_i32 s14, s5
	s_cbranch_scc0 .LBB0_132

.Lpf_done_b:
	s_barrier
	v_lshl_add_u64 v[16:17], v[70:71], 0, s[20:21]
	v_lshl_add_u64 v[18:19], s[18:19], 1, v[72:73]
	global_load_dwordx4 v[28:31], v[16:17], off offset:2048
	s_nop 0
	global_load_dwordx4 v[16:19], v[18:19], off
	s_add_i32 s17, s17, 1
	v_cmp_lt_i32_e32 vcc, s17, v98
	s_cbranch_vccz .Lwrap_b

.LBB0_136:
	s_cmp_lg_u32 s14, 0
	s_cbranch_scc0 .LBB0_160
	s_add_i32 s15, s5, -2
	s_cmp_lg_u32 s14, s15
	s_cbranch_scc0 .LBB0_138
.LBB0_139:
	v_sub_u32_e32 v102, v97, v99
	v_add_u32_e32 v102, s14, v102
	v_cmp_lt_u32_e32 vcc, 7, v102
	s_cbranch_vccnz .Linact_b
	v_lshl_add_u32 v137, v102, 12, v78
	ds_read_b128 v[198:201], v137 offset:39936
	ds_read_b128 v[202:205], v137 offset:40960
	ds_read_b128 v[206:209], v137 offset:41984
	ds_read_b128 v[232:235], v137 offset:43008
	s_waitcnt lgkmcnt(4)
	v_mfma_f32_16x16x32_bf16 v[104:107], v[166:169], v[8:11], v[140:143]
	v_add_f32_e32 v112, v112, v148
	v_add_f32_e32 v113, v113, v149
	v_mfma_f32_16x16x32_bf16 v[108:111], v[174:177], v[8:11], v[140:143]
	v_add_f32_e32 v114, v114, v150
	v_add_f32_e32 v115, v115, v151
	v_mfma_f32_16x16x32_bf16 v[104:107], v[170:173], v[12:15], v[104:107]
	v_add_f32_e32 v116, v116, v158
	v_add_f32_e32 v117, v117, v159
	v_mfma_f32_16x16x32_bf16 v[108:111], v[178:181], v[12:15], v[108:111]
	v_add_f32_e32 v118, v118, v160
	v_add_f32_e32 v119, v119, v161
	ds_read_b128 v[236:239], v83 offset:18432
	ds_read_b128 v[240:243], v83 offset:18688
	ds_read_b128 v[244:247], v83 offset:18944
	ds_read_b128 v[228:231], v83 offset:19200
	v_mfma_f32_16x16x32_bf16 v[112:115], v[182:185], v[8:11], v[112:115]
	v_mfma_f32_16x16x32_bf16 v[116:119], v[190:193], v[8:11], v[116:119]
	v_mfma_f32_16x16x32_bf16 v[112:115], v[186:189], v[12:15], v[112:115]
	v_mfma_f32_16x16x32_bf16 v[116:119], v[194:197], v[12:15], v[116:119]
	v_max3_f32 v121, v104, v105, v106
	v_max3_f32 v122, v108, v109, v110
	v_max3_f32 v121, v121, v107, v111
	s_nop 3
	v_max3_f32 v123, v112, v113, v114
	v_max3_f32 v122, v122, v116, v117
	v_max3_f32 v121, v121, v115, v118
	v_max3_f32 v121, v121, v122, v123
	v_max_f32_e32 v121, v121, v119
	v_cmp_lt_f32_e32 vcc, 0x41000000, v121
	s_cbranch_vccnz .Lrare_b
.Lback_b:
	v_exp_f32_e32 v104, v104
	v_exp_f32_e32 v105, v105
	v_exp_f32_e32 v106, v106
	v_exp_f32_e32 v107, v107
	v_exp_f32_e32 v108, v108
	v_exp_f32_e32 v109, v109
	v_exp_f32_e32 v110, v110
	v_exp_f32_e32 v111, v111
	v_exp_f32_e32 v112, v112
	v_exp_f32_e32 v113, v113
	v_exp_f32_e32 v114, v114
	v_exp_f32_e32 v115, v115
	v_exp_f32_e32 v116, v116
	v_exp_f32_e32 v117, v117
	v_exp_f32_e32 v118, v118
	v_exp_f32_e32 v119, v119
	v_cvt_pk_bf16_f32 v124, v104, v105
	v_cvt_pk_bf16_f32 v125, v106, v107
	v_cvt_pk_bf16_f32 v126, v108, v109
	v_cvt_pk_bf16_f32 v127, v110, v111
	v_cvt_pk_bf16_f32 v128, v112, v113
	v_cvt_pk_bf16_f32 v129, v114, v115
	v_cvt_pk_bf16_f32 v130, v116, v117
	v_cvt_pk_bf16_f32 v131, v118, v119
	s_waitcnt lgkmcnt(4)
	v_mfma_f32_16x16x32_bf16 v[32:35], v[198:201], v[124:127], v[32:35]
	v_mfma_f32_16x16x32_bf16 v[36:39], v[202:205], v[124:127], v[36:39]
	v_mfma_f32_16x16x32_bf16 v[40:43], v[206:209], v[124:127], v[40:43]
	v_mfma_f32_16x16x32_bf16 v[44:47], v[232:235], v[124:127], v[44:47]
	v_mfma_f32_16x16x32_bf16 v[132:135], v[144:147], v[124:127], v[132:135]
	s_waitcnt lgkmcnt(0)
	v_mfma_f32_16x16x32_bf16 v[32:35], v[236:239], v[128:131], v[32:35]
	v_mfma_f32_16x16x32_bf16 v[36:39], v[240:243], v[128:131], v[36:39]
	v_mfma_f32_16x16x32_bf16 v[132:135], v[144:147], v[128:131], v[132:135]
	v_mfma_f32_16x16x32_bf16 v[40:43], v[244:247], v[128:131], v[40:43]
	v_mfma_f32_16x16x32_bf16 v[44:47], v[228:231], v[128:131], v[44:47]
	s_add_i32 s15, s5, -1
	s_cmp_lg_u32 s14, s15
	s_cbranch_scc0 .LBB0_155

.Lpf_done_c:
	s_barrier
	v_lshl_add_u64 v[20:21], v[70:71], 0, s[20:21]
	v_lshl_add_u64 v[22:23], s[18:19], 1, v[72:73]
	global_load_dwordx4 v[24:27], v[20:21], off offset:2048
	s_nop 0
	global_load_dwordx4 v[20:23], v[22:23], off
	s_add_i32 s15, s17, 1
	v_cmp_lt_i32_e32 vcc, s15, v98
	s_cbranch_vccz .Lwrap_c

.LBB0_146:
	s_cmp_lg_u32 s14, 0
	s_cbranch_scc0 .LBB0_161
	s_add_i32 s17, s5, -2
	s_cmp_lg_u32 s14, s17
	s_cbranch_scc0 .LBB0_148
.LBB0_149:
	v_sub_u32_e32 v102, v97, v99
	v_add_u32_e32 v102, s14, v102
	v_cmp_lt_u32_e32 vcc, 7, v102
	s_cbranch_vccnz .Linact_c
	v_lshl_add_u32 v137, v102, 12, v78
	ds_read_b128 v[198:201], v137 offset:39936
	ds_read_b128 v[202:205], v137 offset:40960
	ds_read_b128 v[206:209], v137 offset:41984
	ds_read_b128 v[232:235], v137 offset:43008
	s_waitcnt lgkmcnt(4)
	v_mfma_f32_16x16x32_bf16 v[104:107], v[166:169], v[8:11], v[140:143]
	v_add_f32_e32 v112, v112, v148
	v_add_f32_e32 v113, v113, v149
	v_mfma_f32_16x16x32_bf16 v[108:111], v[174:177], v[8:11], v[140:143]
	v_add_f32_e32 v114, v114, v150
	v_add_f32_e32 v115, v115, v151
	v_mfma_f32_16x16x32_bf16 v[104:107], v[170:173], v[12:15], v[104:107]
	v_add_f32_e32 v116, v116, v158
	v_add_f32_e32 v117, v117, v159
	v_mfma_f32_16x16x32_bf16 v[108:111], v[178:181], v[12:15], v[108:111]
	v_add_f32_e32 v118, v118, v160
	v_add_f32_e32 v119, v119, v161
	ds_read_b128 v[236:239], v83 offset:36864
	ds_read_b128 v[240:243], v83 offset:37120
	ds_read_b128 v[244:247], v83 offset:37376
	ds_read_b128 v[228:231], v83 offset:37632
	v_mfma_f32_16x16x32_bf16 v[112:115], v[182:185], v[8:11], v[112:115]
	v_mfma_f32_16x16x32_bf16 v[116:119], v[190:193], v[8:11], v[116:119]
	v_mfma_f32_16x16x32_bf16 v[112:115], v[186:189], v[12:15], v[112:115]
	v_mfma_f32_16x16x32_bf16 v[116:119], v[194:197], v[12:15], v[116:119]
	v_max3_f32 v121, v104, v105, v106
	v_max3_f32 v122, v108, v109, v110
	v_max3_f32 v121, v121, v107, v111
	s_nop 3
	v_max3_f32 v123, v112, v113, v114
	v_max3_f32 v122, v122, v116, v117
	v_max3_f32 v121, v121, v115, v118
	v_max3_f32 v121, v121, v122, v123
	v_max_f32_e32 v121, v121, v119
	v_cmp_lt_f32_e32 vcc, 0x41000000, v121
	s_cbranch_vccnz .Lrare_c
.Lback_c:
	v_exp_f32_e32 v104, v104
	v_exp_f32_e32 v105, v105
	v_exp_f32_e32 v106, v106
	v_exp_f32_e32 v107, v107
	v_exp_f32_e32 v108, v108
	v_exp_f32_e32 v109, v109
	v_exp_f32_e32 v110, v110
	v_exp_f32_e32 v111, v111
	v_exp_f32_e32 v112, v112
	v_exp_f32_e32 v113, v113
	v_exp_f32_e32 v114, v114
	v_exp_f32_e32 v115, v115
	v_exp_f32_e32 v116, v116
	v_exp_f32_e32 v117, v117
	v_exp_f32_e32 v118, v118
	v_exp_f32_e32 v119, v119
	v_cvt_pk_bf16_f32 v124, v104, v105
	v_cvt_pk_bf16_f32 v125, v106, v107
	v_cvt_pk_bf16_f32 v126, v108, v109
	v_cvt_pk_bf16_f32 v127, v110, v111
	v_cvt_pk_bf16_f32 v128, v112, v113
	v_cvt_pk_bf16_f32 v129, v114, v115
	v_cvt_pk_bf16_f32 v130, v116, v117
	v_cvt_pk_bf16_f32 v131, v118, v119
	s_waitcnt lgkmcnt(4)
	v_mfma_f32_16x16x32_bf16 v[32:35], v[198:201], v[124:127], v[32:35]
	v_mfma_f32_16x16x32_bf16 v[36:39], v[202:205], v[124:127], v[36:39]
	v_mfma_f32_16x16x32_bf16 v[40:43], v[206:209], v[124:127], v[40:43]
	v_mfma_f32_16x16x32_bf16 v[44:47], v[232:235], v[124:127], v[44:47]
	v_mfma_f32_16x16x32_bf16 v[132:135], v[144:147], v[124:127], v[132:135]
	s_waitcnt lgkmcnt(0)
	v_mfma_f32_16x16x32_bf16 v[32:35], v[236:239], v[128:131], v[32:35]
	v_mfma_f32_16x16x32_bf16 v[36:39], v[240:243], v[128:131], v[36:39]
	v_mfma_f32_16x16x32_bf16 v[132:135], v[144:147], v[128:131], v[132:135]
	v_mfma_f32_16x16x32_bf16 v[40:43], v[244:247], v[128:131], v[40:43]
	v_mfma_f32_16x16x32_bf16 v[44:47], v[228:231], v[128:131], v[44:47]
	s_add_i32 s17, s5, -1
	s_cmp_lg_u32 s14, s17
	s_cbranch_scc0 .LBB0_157

.Lpf_skip_b:
	s_waitcnt lgkmcnt(0)
	s_branch .Lpf_done_b

.Lwrap_a:
	s_add_i32 s4, s4, 1
	s_lshl_b32 s16, s4, 1
	v_med3_i32 v98, s16, 4, 28
	s_or_b32 s16, s16, 1
	v_med3_i32 v102, s16, 4, 28
	v_readfirstlane_b32 s15, v98
	v_sub_u32_e32 v98, v102, v98
	s_add_i32 s15, s15, -4
	v_add_u32_e32 v98, 8, v98
	s_mov_b32 s17, 0
	s_cmp_gt_i32 s1, 15
	s_cbranch_scc0 .LBB0_126
	s_branch .LBB0_133
.LBB0_128:
	s_cmp_eq_u32 s1, 15
	s_cselect_b32 s16, 0, 0x80
	s_waitcnt vmcnt(2)
	v_or_b32_e32 v0, s16, v63
	v_add_u32_e32 v0, s2, v0
	v_ashrrev_i32_e32 v1, 31, v0
	v_lshlrev_b64 v[0:1], 12, v[0:1]
	s_waitcnt vmcnt(2)
	v_lshl_add_u64 v[4:5], v[74:75], 0, v[0:1]
	global_load_dwordx4 v[0:3], v[4:5], off
	s_nop 0
	global_load_dwordx4 v[4:7], v[4:5], off offset:64
	s_branch .LBB0_129
.Linact_a:
	s_add_i32 s16, s5, -1
	s_cmp_lg_u32 s14, s16
	s_cbranch_scc0 .LBB0_153
	s_branch .LBB0_131
.LBB0_132:
	s_add_i32 s1, s1, 1
	s_lshl_b32 s2, s1, 1
	s_or_b32 s5, s2, 1
	v_med3_i32 v99, s2, 4, 28
	v_med3_i32 v102, s5, 4, 28
	v_readfirstlane_b32 s13, v99
	v_readfirstlane_b32 s5, v102
	s_sub_i32 s5, s5, s13
	s_add_i32 s13, s2, s9
	v_add_u32_e32 v97, -4, v99
	v_add_u32_e32 v103, -4, v102
	s_lshl_b32 s2, s13, 6
	s_add_i32 s5, s5, 8
	v_cndmask_b32_e64 v99, v103, v97, s[40:41]
	s_add_i32 s2, s2, s0
	s_mov_b32 s14, 0
	s_branch .LBB0_133
.LBB0_153:
	s_nop 7
	v_mov_b32_e32 v102, v132
	v_div_scale_f32 v103, s[18:19], v102, v102, 1.0
	v_rcp_f32_e32 v104, v103
	s_nop 0
	v_fma_f32 v105, -v103, v104, 1.0
	v_fmac_f32_e32 v104, v105, v104
	v_div_scale_f32 v105, vcc, 1.0, v102, 1.0
	v_mul_f32_e32 v106, v105, v104
	v_fma_f32 v107, -v103, v106, v105
	v_fmac_f32_e32 v106, v107, v104
	v_fma_f32 v103, -v103, v106, v105
	v_div_fmas_f32 v103, v103, v104, v106
	v_add_u32_e32 v104, s2, v63
	v_div_fixup_f32 v102, v103, v102, 1.0
	v_ashrrev_i32_e32 v105, 31, v104
	v_lshlrev_b64 v[104:105], 11, v[104:105]
	v_pk_mul_f32 v[108:109], v[32:33], v[102:103] op_sel_hi:[1,0]
	v_lshl_add_u64 v[104:105], v[76:77], 0, v[104:105]
	v_pk_mul_f32 v[106:107], v[34:35], v[102:103] op_sel_hi:[1,0]
	v_cvt_pk_bf16_f32 v108, v108, v109
	s_nop 0
	v_cvt_pk_bf16_f32 v109, v106, v107
	global_store_dwordx2 v[104:105], v[108:109], off
	v_pk_mul_f32 v[108:109], v[36:37], v[102:103] op_sel_hi:[1,0]
	v_pk_mul_f32 v[106:107], v[38:39], v[102:103] op_sel_hi:[1,0]
	v_cvt_pk_bf16_f32 v108, v108, v109
	s_nop 0
	v_cvt_pk_bf16_f32 v109, v106, v107
	global_store_dwordx2 v[104:105], v[108:109], off offset:32
	v_pk_mul_f32 v[106:107], v[42:43], v[102:103] op_sel_hi:[1,0]
	v_pk_mul_f32 v[108:109], v[40:41], v[102:103] op_sel_hi:[1,0]
	s_nop 0
	v_cvt_pk_bf16_f32 v108, v108, v109
	v_cvt_pk_bf16_f32 v109, v106, v107
	v_pk_mul_f32 v[106:107], v[46:47], v[102:103] op_sel_hi:[1,0]
	v_pk_mul_f32 v[102:103], v[44:45], v[102:103] op_sel_hi:[1,0]
	global_store_dwordx2 v[104:105], v[108:109], off offset:64
	v_cvt_pk_bf16_f32 v102, v102, v103
	v_cvt_pk_bf16_f32 v103, v106, v107
	global_store_dwordx2 v[104:105], v[102:103], off offset:96
	s_add_i32 s14, s14, 1
	s_cmp_lt_i32 s14, s5
	s_cbranch_scc0 .LBB0_132
	s_branch .LBB0_133
.Lwrap_b:
	s_add_i32 s4, s4, 1
	s_lshl_b32 s15, s4, 1
	v_med3_i32 v98, s15, 4, 28
	s_or_b32 s15, s15, 1
	v_med3_i32 v102, s15, 4, 28
	v_readfirstlane_b32 s16, v98
	v_sub_u32_e32 v98, v102, v98
	s_add_i32 s16, s16, -4
	v_add_u32_e32 v98, 8, v98
	s_mov_b32 s17, 0
	s_cmp_gt_i32 s1, 15
	s_cbranch_scc0 .LBB0_136
	s_branch .LBB0_143
.LBB0_138:
	s_cmp_eq_u32 s1, 15
	s_cselect_b32 s15, 0, 0x80
	s_add_i32 s15, s15, s2
	s_waitcnt vmcnt(2)
	v_add_u32_e32 v0, s15, v63
	v_ashrrev_i32_e32 v1, 31, v0
	v_lshlrev_b64 v[0:1], 12, v[0:1]
	s_waitcnt vmcnt(2)
	v_lshl_add_u64 v[4:5], v[74:75], 0, v[0:1]
	global_load_dwordx4 v[0:3], v[4:5], off
	s_nop 0
	global_load_dwordx4 v[4:7], v[4:5], off offset:64
	s_branch .LBB0_139
.Linact_b:
	s_add_i32 s15, s5, -1
	s_cmp_lg_u32 s14, s15
	s_cbranch_scc0 .LBB0_155
	s_branch .LBB0_141
.LBB0_142:
	s_add_i32 s1, s1, 1
	s_lshl_b32 s2, s1, 1
	s_or_b32 s5, s2, 1
	v_med3_i32 v99, s2, 4, 28
	v_med3_i32 v102, s5, 4, 28
	v_readfirstlane_b32 s13, v99
	v_readfirstlane_b32 s5, v102
	s_sub_i32 s5, s5, s13
	s_add_i32 s13, s2, s9
	v_add_u32_e32 v97, -4, v99
	v_add_u32_e32 v103, -4, v102
	s_lshl_b32 s2, s13, 6
	s_add_i32 s5, s5, 8
	v_cndmask_b32_e64 v99, v103, v97, s[40:41]
	s_add_i32 s2, s2, s0
	s_mov_b32 s14, 0
	s_branch .LBB0_143
.LBB0_155:
	s_nop 7
	v_mov_b32_e32 v102, v132
	v_div_scale_f32 v103, s[18:19], v102, v102, 1.0
	v_rcp_f32_e32 v104, v103
	s_nop 0
	v_fma_f32 v105, -v103, v104, 1.0
	v_fmac_f32_e32 v104, v105, v104
	v_div_scale_f32 v105, vcc, 1.0, v102, 1.0
	v_mul_f32_e32 v106, v105, v104
	v_fma_f32 v107, -v103, v106, v105
	v_fmac_f32_e32 v106, v107, v104
	v_fma_f32 v103, -v103, v106, v105
	v_div_fmas_f32 v103, v103, v104, v106
	v_add_u32_e32 v104, s2, v63
	v_div_fixup_f32 v102, v103, v102, 1.0
	v_ashrrev_i32_e32 v105, 31, v104
	v_lshlrev_b64 v[104:105], 11, v[104:105]
	v_pk_mul_f32 v[108:109], v[32:33], v[102:103] op_sel_hi:[1,0]
	v_lshl_add_u64 v[104:105], v[76:77], 0, v[104:105]
	v_pk_mul_f32 v[106:107], v[34:35], v[102:103] op_sel_hi:[1,0]
	v_cvt_pk_bf16_f32 v108, v108, v109
	s_nop 0
	v_cvt_pk_bf16_f32 v109, v106, v107
	global_store_dwordx2 v[104:105], v[108:109], off
	v_pk_mul_f32 v[108:109], v[36:37], v[102:103] op_sel_hi:[1,0]
	v_pk_mul_f32 v[106:107], v[38:39], v[102:103] op_sel_hi:[1,0]
	v_cvt_pk_bf16_f32 v108, v108, v109
	s_nop 0
	v_cvt_pk_bf16_f32 v109, v106, v107
	global_store_dwordx2 v[104:105], v[108:109], off offset:32
	v_pk_mul_f32 v[106:107], v[42:43], v[102:103] op_sel_hi:[1,0]
	v_pk_mul_f32 v[108:109], v[40:41], v[102:103] op_sel_hi:[1,0]
	s_nop 0
	v_cvt_pk_bf16_f32 v108, v108, v109
	v_cvt_pk_bf16_f32 v109, v106, v107
	v_pk_mul_f32 v[106:107], v[46:47], v[102:103] op_sel_hi:[1,0]
	v_pk_mul_f32 v[102:103], v[44:45], v[102:103] op_sel_hi:[1,0]
	global_store_dwordx2 v[104:105], v[108:109], off offset:64
	v_cvt_pk_bf16_f32 v102, v102, v103
	v_cvt_pk_bf16_f32 v103, v106, v107
	global_store_dwordx2 v[104:105], v[102:103], off offset:96
	s_add_i32 s14, s14, 1
	s_cmp_lt_i32 s14, s5
	s_cbranch_scc0 .LBB0_142
	s_branch .LBB0_143
.Lwrap_c:
	s_add_i32 s4, s4, 1
	s_lshl_b32 s15, s4, 1
	v_med3_i32 v98, s15, 4, 28
	s_or_b32 s15, s15, 1
	v_med3_i32 v102, s15, 4, 28
	v_readfirstlane_b32 s16, v98
	v_sub_u32_e32 v98, v102, v98
	s_add_i32 s16, s16, -4
	v_add_u32_e32 v98, 8, v98
	s_mov_b32 s15, 0
	s_cmp_gt_i32 s1, 15
	s_cbranch_scc1 .LBB0_122
	s_branch .LBB0_146
.LBB0_148:
	s_cmp_eq_u32 s1, 15
	s_cselect_b32 s17, 0, 0x80
	s_add_i32 s17, s17, s2
	s_waitcnt vmcnt(2)
	v_add_u32_e32 v0, s17, v63
	v_ashrrev_i32_e32 v1, 31, v0
	v_lshlrev_b64 v[0:1], 12, v[0:1]
	s_waitcnt vmcnt(2)
	v_lshl_add_u64 v[4:5], v[74:75], 0, v[0:1]
	global_load_dwordx4 v[0:3], v[4:5], off
	s_nop 0
	global_load_dwordx4 v[4:7], v[4:5], off offset:64
	s_branch .LBB0_149
.Linact_c:
	s_add_i32 s17, s5, -1
	s_cmp_lg_u32 s14, s17
	s_cbranch_scc0 .LBB0_157
	s_branch .LBB0_151
